# K-loops: first 4 MFMAs of each cluster issued before the phase barrier (register-only work queued across the barrier hand-over) on v38
# speedup vs baseline: 1.0210x; 1.0210x over previous
; #define PG8_STAGE(bufoff, gbase, voff) do { _Pragma("unroll") for (int _i = 0; _i < 2; ++_i) \
;         __builtin_amdgcn_global_load_lds((const unsigned*)((const char*)(gbase) + (voff)[_i]), (PG8_LAS unsigned*)(lds + (bufoff) + ldsw + _i * 8192), 16, 0, 0); } while (0)
; #define PG8_LDA(dst, b, h) do { _Pragma("unroll") for (int m = 0; m < 4; ++m) _Pragma("unroll") for (int k = 0; k < 2; ++k) dst[m][k] = *(const PG8_LAS bf16x8*)(lds + PG8_SA(b, h) + aoff + m * 2048 + k * 1024); } while (0)
; #define PG8_MMA(ai, bj, At, Bt) do { __builtin_amdgcn_s_setprio(1); _Pragma("unroll") for (int m = 0; m < 4; ++m) _Pragma("unroll") for (int n = 0; n < 2; ++n) _Pragma("unroll") for (int k = 0; k < 2; ++k) \
;         acc[ai][bj][m][n] = __builtin_amdgcn_mfma_f32_16x16x32_bf16(Bt[n][k], At[m][k], acc[ai][bj][m][n], 0, 0, 0); __builtin_amdgcn_s_setprio(0); } while (0)
; #define PG8_WAIT_V(n) asm volatile("s_waitcnt vmcnt(" #n ")" ::: "memory")
; #define PG8_WAIT_L(n) asm volatile("s_waitcnt lgkmcnt(" #n ")" ::: "memory")
; #define PG8_BAR __builtin_amdgcn_s_barrier()
; #define PG8_SCHED __builtin_amdgcn_sched_barrier(0)
; template <class Epi, class Sched, bool ALIGN_EPI = false, bool SP2 = false>
; __device__ __forceinline__ void gemm_phase(PG8_LAS unsigned char* lds, const Gemm g, const Sched& S, const Epi& E, const int tid) {
;     ...
;             PG8_WAIT_V(8); PG8_WAIT_L(0); PG8_BAR; PG8_MMA(0, 0, At, B0); PG8_MMA(0, 1, At, B1); PG8_BAR; PG8_SCHED;
;             PG8_LDA(At, 0, 1); PG8_STAGE(PG8_SB(0, 0), b2, voffB); PG8_STAGE(PG8_SB(0, 1), b2 + hstepB, voffB); PG8_STAGE(PG8_SA(0, 0), a2, voffA);
;             PG8_WAIT_V(8); PG8_WAIT_L(0); PG8_BAR; PG8_MMA(1, 0, At, B0); PG8_MMA(1, 1, At, B1); PG8_BAR; PG8_SCHED;
.Lkw_up_0:
	s_waitcnt lgkmcnt(0)
	v_mfma_f32_16x16x32_bf16 v[124:127], v[148:151], v[208:211], v[124:127]
	v_mfma_f32_16x16x32_bf16 v[120:123], v[162:165], v[208:211], v[120:123]
	v_mfma_f32_16x16x32_bf16 v[108:111], v[148:151], v[216:219], v[108:111]
	v_mfma_f32_16x16x32_bf16 v[104:107], v[162:165], v[216:219], v[104:107]
	s_barrier
	s_setprio 1
	s_waitcnt lgkmcnt(0)
	v_mfma_f32_16x16x32_bf16 v[92:95], v[148:151], v[224:227], v[92:95]
	v_mfma_f32_16x16x32_bf16 v[88:91], v[162:165], v[224:227], v[88:91]
	v_mfma_f32_16x16x32_bf16 v[76:79], v[148:151], v[232:235], v[76:79]
	v_mfma_f32_16x16x32_bf16 v[72:75], v[162:165], v[232:235], v[72:75]
	v_mfma_f32_16x16x32_bf16 v[124:127], v[158:161], v[212:215], v[124:127]
	v_mfma_f32_16x16x32_bf16 v[120:123], v[188:191], v[212:215], v[120:123]
	v_mfma_f32_16x16x32_bf16 v[108:111], v[158:161], v[220:223], v[108:111]
	v_mfma_f32_16x16x32_bf16 v[104:107], v[188:191], v[220:223], v[104:107]
	v_mfma_f32_16x16x32_bf16 v[92:95], v[158:161], v[228:231], v[92:95]
	v_mfma_f32_16x16x32_bf16 v[88:91], v[188:191], v[228:231], v[88:91]
	v_mfma_f32_16x16x32_bf16 v[76:79], v[158:161], v[236:239], v[76:79]
	v_mfma_f32_16x16x32_bf16 v[72:75], v[188:191], v[236:239], v[72:75]
	s_setprio 0
	s_setprio 1
	v_mfma_f32_16x16x32_bf16 v[116:119], v[192:195], v[208:211], v[116:119]
	v_mfma_f32_16x16x32_bf16 v[112:115], v[200:203], v[208:211], v[112:115]
	v_mfma_f32_16x16x32_bf16 v[100:103], v[192:195], v[216:219], v[100:103]
	v_mfma_f32_16x16x32_bf16 v[96:99], v[200:203], v[216:219], v[96:99]
	v_mfma_f32_16x16x32_bf16 v[84:87], v[192:195], v[224:227], v[84:87]
	v_mfma_f32_16x16x32_bf16 v[80:83], v[200:203], v[224:227], v[80:83]
	v_mfma_f32_16x16x32_bf16 v[68:71], v[192:195], v[232:235], v[68:71]
	v_mfma_f32_16x16x32_bf16 v[64:67], v[200:203], v[232:235], v[64:67]
	v_mfma_f32_16x16x32_bf16 v[116:119], v[196:199], v[212:215], v[116:119]
	v_mfma_f32_16x16x32_bf16 v[112:115], v[204:207], v[212:215], v[112:115]
	v_mfma_f32_16x16x32_bf16 v[100:103], v[196:199], v[220:223], v[100:103]
	v_mfma_f32_16x16x32_bf16 v[96:99], v[204:207], v[220:223], v[96:99]
	v_mfma_f32_16x16x32_bf16 v[84:87], v[196:199], v[228:231], v[84:87]
	v_mfma_f32_16x16x32_bf16 v[80:83], v[204:207], v[228:231], v[80:83]
	v_mfma_f32_16x16x32_bf16 v[68:71], v[196:199], v[236:239], v[68:71]
	v_mfma_f32_16x16x32_bf16 v[64:67], v[204:207], v[236:239], v[64:67]
	s_setprio 0
	s_barrier
	s_add_i32 s36, s36, s68
	v_lshl_add_u64 v[166:167], s[18:19], 0, v[140:141]
	s_mov_b32 m0, s36
	ds_read_b128 v[208:211], v157 offset:16384
	ds_read_b128 v[212:215], v157 offset:17408
	ds_read_b128 v[216:219], v157 offset:18432
	ds_read_b128 v[220:223], v157 offset:19456
	ds_read_b128 v[224:227], v157 offset:20480
	ds_read_b128 v[228:231], v157 offset:21504
	ds_read_b128 v[232:235], v157 offset:22528
	ds_read_b128 v[236:239], v157 offset:23552
	global_load_lds_dwordx4 v[166:167], off
	s_add_i32 m0, s36, 0x2000
	s_add_u32 s36, s18, 0x40000
	v_lshl_add_u64 v[240:241], s[18:19], 0, v[136:137]
	s_addc_u32 s37, s19, 0
	s_add_i32 s38, s38, s68
	global_load_lds_dwordx4 v[240:241], off
	v_lshl_add_u64 v[242:243], s[36:37], 0, v[140:141]
	s_mov_b32 m0, s38
	v_lshl_add_u64 v[244:245], s[22:23], 0, v[138:139]
	global_load_lds_dwordx4 v[242:243], off
	v_lshl_add_u64 v[242:243], s[36:37], 0, v[136:137]
	s_add_i32 m0, s38, 0x2000
	s_nop 0
	global_load_lds_dwordx4 v[242:243], off
	v_lshl_add_u64 v[242:243], s[22:23], 0, v[142:143]
	s_mov_b32 m0, s69
	s_nop 0
	global_load_lds_dwordx4 v[242:243], off
	s_mov_b32 m0, s70
	s_nop 0
	global_load_lds_dwordx4 v[244:245], off
	s_cmp_eq_u32 s99, 1
	s_cbranch_scc1 .Lkw_up_1
	s_waitcnt vmcnt(8)
.Lkw_up_1:
	s_waitcnt lgkmcnt(0)
	v_mfma_f32_16x16x32_bf16 v[60:63], v[148:151], v[208:211], v[60:63]
	v_mfma_f32_16x16x32_bf16 v[56:59], v[162:165], v[208:211], v[56:59]
	v_mfma_f32_16x16x32_bf16 v[44:47], v[148:151], v[216:219], v[44:47]
	v_mfma_f32_16x16x32_bf16 v[40:43], v[162:165], v[216:219], v[40:43]
	s_barrier
	s_setprio 1
	s_waitcnt lgkmcnt(0)
	v_mfma_f32_16x16x32_bf16 v[28:31], v[148:151], v[224:227], v[28:31]
	v_mfma_f32_16x16x32_bf16 v[24:27], v[162:165], v[224:227], v[24:27]
	v_mfma_f32_16x16x32_bf16 v[12:15], v[148:151], v[232:235], v[12:15]
	v_mfma_f32_16x16x32_bf16 v[8:11], v[162:165], v[232:235], v[8:11]
	v_mfma_f32_16x16x32_bf16 v[60:63], v[158:161], v[212:215], v[60:63]
	v_mfma_f32_16x16x32_bf16 v[56:59], v[188:191], v[212:215], v[56:59]
	v_mfma_f32_16x16x32_bf16 v[44:47], v[158:161], v[220:223], v[44:47]
	v_mfma_f32_16x16x32_bf16 v[40:43], v[188:191], v[220:223], v[40:43]
	v_mfma_f32_16x16x32_bf16 v[28:31], v[158:161], v[228:231], v[28:31]
	v_mfma_f32_16x16x32_bf16 v[24:27], v[188:191], v[228:231], v[24:27]
	v_mfma_f32_16x16x32_bf16 v[12:15], v[158:161], v[236:239], v[12:15]
	v_mfma_f32_16x16x32_bf16 v[8:11], v[188:191], v[236:239], v[8:11]
	s_setprio 0
	s_setprio 1
	v_mfma_f32_16x16x32_bf16 v[52:55], v[192:195], v[208:211], v[52:55]
	v_mfma_f32_16x16x32_bf16 v[48:51], v[200:203], v[208:211], v[48:51]
	v_mfma_f32_16x16x32_bf16 v[36:39], v[192:195], v[216:219], v[36:39]
	v_mfma_f32_16x16x32_bf16 v[32:35], v[200:203], v[216:219], v[32:35]
	v_mfma_f32_16x16x32_bf16 v[20:23], v[192:195], v[224:227], v[20:23]
	v_mfma_f32_16x16x32_bf16 v[16:19], v[200:203], v[224:227], v[16:19]
	v_mfma_f32_16x16x32_bf16 v[4:7], v[192:195], v[232:235], v[4:7]
	v_mfma_f32_16x16x32_bf16 v[0:3], v[200:203], v[232:235], v[0:3]
	v_mfma_f32_16x16x32_bf16 v[52:55], v[196:199], v[212:215], v[52:55]
	v_mfma_f32_16x16x32_bf16 v[48:51], v[204:207], v[212:215], v[48:51]
	v_mfma_f32_16x16x32_bf16 v[36:39], v[196:199], v[220:223], v[36:39]
	v_mfma_f32_16x16x32_bf16 v[32:35], v[204:207], v[220:223], v[32:35]
	v_mfma_f32_16x16x32_bf16 v[20:23], v[196:199], v[228:231], v[20:23]
	v_mfma_f32_16x16x32_bf16 v[16:19], v[204:207], v[228:231], v[16:19]
	v_mfma_f32_16x16x32_bf16 v[4:7], v[196:199], v[236:239], v[4:7]
	v_mfma_f32_16x16x32_bf16 v[0:3], v[204:207], v[236:239], v[0:3]
	s_setprio 0
	s_barrier
; #define PG8_STAGE(bufoff, gbase, voff) do { _Pragma("unroll") for (int _i = 0; _i < 2; ++_i) \
;         __builtin_amdgcn_global_load_lds((const unsigned*)((const char*)(gbase) + (voff)[_i]), (PG8_LAS unsigned*)(lds + (bufoff) + ldsw + _i * 8192), 16, 0, 0); } while (0)
; #define PG8_LDA(dst, b, h) do { _Pragma("unroll") for (int m = 0; m < 4; ++m) _Pragma("unroll") for (int k = 0; k < 2; ++k) dst[m][k] = *(const PG8_LAS bf16x8*)(lds + PG8_SA(b, h) + aoff + m * 2048 + k * 1024); } while (0)
; #define PG8_LDB(dst, b, h) do { _Pragma("unroll") for (int n = 0; n < 2; ++n) _Pragma("unroll") for (int k = 0; k < 2; ++k) dst[n][k] = *(const PG8_LAS bf16x8*)(lds + PG8_SB(b, h) + boff + n * 2048 + k * 1024); } while (0)
; #define PG8_MMA(ai, bj, At, Bt) do { __builtin_amdgcn_s_setprio(1); _Pragma("unroll") for (int m = 0; m < 4; ++m) _Pragma("unroll") for (int n = 0; n < 2; ++n) _Pragma("unroll") for (int k = 0; k < 2; ++k) \
;         acc[ai][bj][m][n] = __builtin_amdgcn_mfma_f32_16x16x32_bf16(Bt[n][k], At[m][k], acc[ai][bj][m][n], 0, 0, 0); __builtin_amdgcn_s_setprio(0); } while (0)
; #define PG8_WAIT_V(n) asm volatile("s_waitcnt vmcnt(" #n ")" ::: "memory")
; #define PG8_WAIT_L(n) asm volatile("s_waitcnt lgkmcnt(" #n ")" ::: "memory")
; #define PG8_BAR __builtin_amdgcn_s_barrier()
; #define PG8_SCHED __builtin_amdgcn_sched_barrier(0)
; template <class Epi, class Sched, bool ALIGN_EPI = false, bool SP2 = false>
; __device__ __forceinline__ void gemm_phase(PG8_LAS unsigned char* lds, const Gemm g, const Sched& S, const Epi& E, const int tid) {
;     ...
;             PG8_LDB(B0, 1, 0); PG8_LDB(B1, 1, 1); PG8_SCHED; PG8_LDA(At, 1, 0); PG8_STAGE(PG8_SA(0, 1), a2 + hstepA, voffA);
;             PG8_WAIT_V(8); PG8_WAIT_L(0); PG8_BAR; PG8_MMA(0, 0, At, B0); PG8_MMA(0, 1, At, B1); PG8_BAR; PG8_SCHED;
	s_add_i32 s36, 0, 0x18000
	v_add_u32_e32 v128, s36, v155
	s_add_i32 s37, 0, 0x1c000
	ds_read_b128 v[148:151], v128
	ds_read_b128 v[158:161], v128 offset:1024
	ds_read_b128 v[162:165], v128 offset:2048
	ds_read_b128 v[188:191], v128 offset:3072
	v_add_u32_e32 v128, s37, v155
	ds_read_b128 v[192:195], v128
	ds_read_b128 v[196:199], v128 offset:1024
	ds_read_b128 v[200:203], v128 offset:2048
	ds_read_b128 v[204:207], v128 offset:3072
	s_add_u32 s22, s22, 0x80000
	s_addc_u32 s23, s23, 0
	s_mov_b32 m0, s71
	v_lshl_add_u64 v[246:247], s[22:23], 0, v[142:143]
	ds_read_b128 v[208:211], v157 offset:32768
	ds_read_b128 v[212:215], v157 offset:33792
	ds_read_b128 v[216:219], v157 offset:34816
	ds_read_b128 v[220:223], v157 offset:35840
	ds_read_b128 v[224:227], v157 offset:36864
	ds_read_b128 v[228:231], v157 offset:37888
	ds_read_b128 v[232:235], v157 offset:38912
	ds_read_b128 v[236:239], v157 offset:39936
	global_load_lds_dwordx4 v[246:247], off
	v_lshl_add_u64 v[246:247], s[22:23], 0, v[138:139]
	s_mov_b32 m0, s74
	s_nop 0
	global_load_lds_dwordx4 v[246:247], off
	s_waitcnt vmcnt(8)
	s_waitcnt lgkmcnt(0)
	v_mfma_f32_16x16x32_bf16 v[124:127], v[148:151], v[208:211], v[124:127]
	v_mfma_f32_16x16x32_bf16 v[120:123], v[162:165], v[208:211], v[120:123]
	v_mfma_f32_16x16x32_bf16 v[108:111], v[148:151], v[216:219], v[108:111]
	v_mfma_f32_16x16x32_bf16 v[104:107], v[162:165], v[216:219], v[104:107]
	s_barrier
	s_setprio 1
	s_waitcnt lgkmcnt(0)
	v_mfma_f32_16x16x32_bf16 v[92:95], v[148:151], v[224:227], v[92:95]
	v_mfma_f32_16x16x32_bf16 v[88:91], v[162:165], v[224:227], v[88:91]
	v_mfma_f32_16x16x32_bf16 v[76:79], v[148:151], v[232:235], v[76:79]
	v_mfma_f32_16x16x32_bf16 v[72:75], v[162:165], v[232:235], v[72:75]
	v_mfma_f32_16x16x32_bf16 v[124:127], v[158:161], v[212:215], v[124:127]
	v_mfma_f32_16x16x32_bf16 v[120:123], v[188:191], v[212:215], v[120:123]
	v_mfma_f32_16x16x32_bf16 v[108:111], v[158:161], v[220:223], v[108:111]
	v_mfma_f32_16x16x32_bf16 v[104:107], v[188:191], v[220:223], v[104:107]
	v_mfma_f32_16x16x32_bf16 v[92:95], v[158:161], v[228:231], v[92:95]
	v_mfma_f32_16x16x32_bf16 v[88:91], v[188:191], v[228:231], v[88:91]
	v_mfma_f32_16x16x32_bf16 v[76:79], v[158:161], v[236:239], v[76:79]
	v_mfma_f32_16x16x32_bf16 v[72:75], v[188:191], v[236:239], v[72:75]
	s_setprio 0
	s_setprio 1
	v_mfma_f32_16x16x32_bf16 v[116:119], v[192:195], v[208:211], v[116:119]
	v_mfma_f32_16x16x32_bf16 v[112:115], v[200:203], v[208:211], v[112:115]
	v_mfma_f32_16x16x32_bf16 v[100:103], v[192:195], v[216:219], v[100:103]
	v_mfma_f32_16x16x32_bf16 v[96:99], v[200:203], v[216:219], v[96:99]
	v_mfma_f32_16x16x32_bf16 v[84:87], v[192:195], v[224:227], v[84:87]
	v_mfma_f32_16x16x32_bf16 v[80:83], v[200:203], v[224:227], v[80:83]
	v_mfma_f32_16x16x32_bf16 v[68:71], v[192:195], v[232:235], v[68:71]
	v_mfma_f32_16x16x32_bf16 v[64:67], v[200:203], v[232:235], v[64:67]
	v_mfma_f32_16x16x32_bf16 v[116:119], v[196:199], v[212:215], v[116:119]
	v_mfma_f32_16x16x32_bf16 v[112:115], v[204:207], v[212:215], v[112:115]
	v_mfma_f32_16x16x32_bf16 v[100:103], v[196:199], v[220:223], v[100:103]
	v_mfma_f32_16x16x32_bf16 v[96:99], v[204:207], v[220:223], v[96:99]
	v_mfma_f32_16x16x32_bf16 v[84:87], v[196:199], v[228:231], v[84:87]
	v_mfma_f32_16x16x32_bf16 v[80:83], v[204:207], v[228:231], v[80:83]
	v_mfma_f32_16x16x32_bf16 v[68:71], v[196:199], v[236:239], v[68:71]
	v_mfma_f32_16x16x32_bf16 v[64:67], v[204:207], v[236:239], v[64:67]
	s_setprio 0
	s_barrier
; #define PG8_STAGE(bufoff, gbase, voff) do { _Pragma("unroll") for (int _i = 0; _i < 2; ++_i) \
;         __builtin_amdgcn_global_load_lds((const unsigned*)((const char*)(gbase) + (voff)[_i]), (PG8_LAS unsigned*)(lds + (bufoff) + ldsw + _i * 8192), 16, 0, 0); } while (0)
; #define PG8_LDA(dst, b, h) do { _Pragma("unroll") for (int m = 0; m < 4; ++m) _Pragma("unroll") for (int k = 0; k < 2; ++k) dst[m][k] = *(const PG8_LAS bf16x8*)(lds + PG8_SA(b, h) + aoff + m * 2048 + k * 1024); } while (0)
; #define PG8_MMA(ai, bj, At, Bt) do { __builtin_amdgcn_s_setprio(1); _Pragma("unroll") for (int m = 0; m < 4; ++m) _Pragma("unroll") for (int n = 0; n < 2; ++n) _Pragma("unroll") for (int k = 0; k < 2; ++k) \
;         acc[ai][bj][m][n] = __builtin_amdgcn_mfma_f32_16x16x32_bf16(Bt[n][k], At[m][k], acc[ai][bj][m][n], 0, 0, 0); __builtin_amdgcn_s_setprio(0); } while (0)
; #define PG8_WAIT_V(n) asm volatile("s_waitcnt vmcnt(" #n ")" ::: "memory")
; #define PG8_WAIT_L(n) asm volatile("s_waitcnt lgkmcnt(" #n ")" ::: "memory")
; #define PG8_BAR __builtin_amdgcn_s_barrier()
; #define PG8_SCHED __builtin_amdgcn_sched_barrier(0)
; template <class Epi, class Sched, bool ALIGN_EPI = false, bool SP2 = false>
; __device__ __forceinline__ void gemm_phase(PG8_LAS unsigned char* lds, const Gemm g, const Sched& S, const Epi& E, const int tid) {
;     ...
;         for (int t = 0; t < nt; t += 2) {
;     ...
;             PG8_LDA(At, 1, 1); PG8_STAGE(PG8_SB(1, 0), b3, voffB); PG8_STAGE(PG8_SB(1, 1), b3 + hstepB, voffB); PG8_STAGE(PG8_SA(1, 0), a3, voffA);
;             PG8_WAIT_V(8); PG8_WAIT_L(0); PG8_BAR; PG8_MMA(1, 0, At, B0); PG8_MMA(1, 1, At, B1); PG8_BAR; PG8_SCHED;
	s_add_i32 s22, s36, s68
	v_lshl_add_u64 v[166:167], v[166:167], 0, s[76:77]
	s_mov_b32 m0, s22
	ds_read_b128 v[208:211], v157 offset:49152
	ds_read_b128 v[212:215], v157 offset:50176
	ds_read_b128 v[216:219], v157 offset:51200
	ds_read_b128 v[220:223], v157 offset:52224
	ds_read_b128 v[224:227], v157 offset:53248
	ds_read_b128 v[228:231], v157 offset:54272
	ds_read_b128 v[232:235], v157 offset:55296
	ds_read_b128 v[236:239], v157 offset:56320
	global_load_lds_dwordx4 v[166:167], off
	s_add_i32 m0, s22, 0x2000
	s_add_u32 s18, s18, 0x40080
	v_lshl_add_u64 v[166:167], v[240:241], 0, s[76:77]
	s_addc_u32 s19, s19, 0
	s_add_i32 s22, s37, s68
	global_load_lds_dwordx4 v[166:167], off
	v_lshl_add_u64 v[166:167], s[18:19], 0, v[140:141]
	s_mov_b32 m0, s22
	s_nop 0
	global_load_lds_dwordx4 v[166:167], off
	v_lshl_add_u64 v[166:167], s[18:19], 0, v[136:137]
	s_add_i32 m0, s22, 0x2000
	s_nop 0
	global_load_lds_dwordx4 v[166:167], off
	v_lshl_add_u64 v[166:167], v[242:243], 0, s[76:77]
	s_mov_b32 m0, s84
	s_nop 0
	global_load_lds_dwordx4 v[166:167], off
	v_lshl_add_u64 v[166:167], v[244:245], 0, s[76:77]
	s_mov_b32 m0, s87
	s_nop 0
	global_load_lds_dwordx4 v[166:167], off
	s_waitcnt vmcnt(8)
	s_waitcnt lgkmcnt(0)
	v_mfma_f32_16x16x32_bf16 v[60:63], v[148:151], v[208:211], v[60:63]
	v_mfma_f32_16x16x32_bf16 v[56:59], v[162:165], v[208:211], v[56:59]
	v_mfma_f32_16x16x32_bf16 v[44:47], v[148:151], v[216:219], v[44:47]
	v_mfma_f32_16x16x32_bf16 v[40:43], v[162:165], v[216:219], v[40:43]
	s_barrier
	s_setprio 1
	s_waitcnt lgkmcnt(0)
	v_mfma_f32_16x16x32_bf16 v[28:31], v[148:151], v[224:227], v[28:31]
	v_mfma_f32_16x16x32_bf16 v[24:27], v[162:165], v[224:227], v[24:27]
	v_mfma_f32_16x16x32_bf16 v[12:15], v[148:151], v[232:235], v[12:15]
	v_mfma_f32_16x16x32_bf16 v[8:11], v[162:165], v[232:235], v[8:11]
	v_mfma_f32_16x16x32_bf16 v[60:63], v[158:161], v[212:215], v[60:63]
	v_mfma_f32_16x16x32_bf16 v[56:59], v[188:191], v[212:215], v[56:59]
	v_mfma_f32_16x16x32_bf16 v[44:47], v[158:161], v[220:223], v[44:47]
	v_mfma_f32_16x16x32_bf16 v[40:43], v[188:191], v[220:223], v[40:43]
	v_mfma_f32_16x16x32_bf16 v[28:31], v[158:161], v[228:231], v[28:31]
	v_mfma_f32_16x16x32_bf16 v[24:27], v[188:191], v[228:231], v[24:27]
	v_mfma_f32_16x16x32_bf16 v[12:15], v[158:161], v[236:239], v[12:15]
	v_mfma_f32_16x16x32_bf16 v[8:11], v[188:191], v[236:239], v[8:11]
	s_setprio 0
	s_setprio 1
	v_mfma_f32_16x16x32_bf16 v[52:55], v[192:195], v[208:211], v[52:55]
	v_mfma_f32_16x16x32_bf16 v[48:51], v[200:203], v[208:211], v[48:51]
	v_mfma_f32_16x16x32_bf16 v[36:39], v[192:195], v[216:219], v[36:39]
	v_mfma_f32_16x16x32_bf16 v[32:35], v[200:203], v[216:219], v[32:35]
	v_mfma_f32_16x16x32_bf16 v[20:23], v[192:195], v[224:227], v[20:23]
	v_mfma_f32_16x16x32_bf16 v[16:19], v[200:203], v[224:227], v[16:19]
	v_mfma_f32_16x16x32_bf16 v[4:7], v[192:195], v[232:235], v[4:7]
	v_mfma_f32_16x16x32_bf16 v[0:3], v[200:203], v[232:235], v[0:3]
	v_mfma_f32_16x16x32_bf16 v[52:55], v[196:199], v[212:215], v[52:55]
	v_mfma_f32_16x16x32_bf16 v[48:51], v[204:207], v[212:215], v[48:51]
	v_mfma_f32_16x16x32_bf16 v[36:39], v[196:199], v[220:223], v[36:39]
	v_mfma_f32_16x16x32_bf16 v[32:35], v[204:207], v[220:223], v[32:35]
	v_mfma_f32_16x16x32_bf16 v[20:23], v[196:199], v[228:231], v[20:23]
	v_mfma_f32_16x16x32_bf16 v[16:19], v[204:207], v[228:231], v[16:19]
	v_mfma_f32_16x16x32_bf16 v[4:7], v[196:199], v[236:239], v[4:7]
	v_mfma_f32_16x16x32_bf16 v[0:3], v[204:207], v[236:239], v[0:3]
	s_setprio 0
	s_barrier
	s_add_i32 s31, s31, 2
	s_add_u32 s8, s8, 0x100
	s_addc_u32 s9, s9, 0
	s_add_u32 s29, s29, 0x100
	s_addc_u32 s30, s30, 0
	s_cmp_gt_u32 s31, 13
	s_cbranch_scc0 .LBB0_35
	s_and_b64 vcc, exec, s[10:11]
	s_cbranch_vccz .LBB0_38
	s_barrier

; #define PG8_STAGE(bufoff, gbase, voff) do { _Pragma("unroll") for (int _i = 0; _i < 2; ++_i) \
;         __builtin_amdgcn_global_load_lds((const unsigned*)((const char*)(gbase) + (voff)[_i]), (PG8_LAS unsigned*)(lds + (bufoff) + ldsw + _i * 8192), 16, 0, 0); } while (0)
; #define PG8_LDA(dst, b, h) do { _Pragma("unroll") for (int m = 0; m < 4; ++m) _Pragma("unroll") for (int k = 0; k < 2; ++k) dst[m][k] = *(const PG8_LAS bf16x8*)(lds + PG8_SA(b, h) + aoff + m * 2048 + k * 1024); } while (0)
; #define PG8_MMA(ai, bj, At, Bt) do { __builtin_amdgcn_s_setprio(1); _Pragma("unroll") for (int m = 0; m < 4; ++m) _Pragma("unroll") for (int n = 0; n < 2; ++n) _Pragma("unroll") for (int k = 0; k < 2; ++k) \
;         acc[ai][bj][m][n] = __builtin_amdgcn_mfma_f32_16x16x32_bf16(Bt[n][k], At[m][k], acc[ai][bj][m][n], 0, 0, 0); __builtin_amdgcn_s_setprio(0); } while (0)
; #define PG8_WAIT_V(n) asm volatile("s_waitcnt vmcnt(" #n ")" ::: "memory")
; #define PG8_WAIT_L(n) asm volatile("s_waitcnt lgkmcnt(" #n ")" ::: "memory")
; #define PG8_BAR __builtin_amdgcn_s_barrier()
; #define PG8_SCHED __builtin_amdgcn_sched_barrier(0)
; template <class Epi, class Sched, bool ALIGN_EPI = false, bool SP2 = false>
; __device__ __forceinline__ void gemm_phase(PG8_LAS unsigned char* lds, const Gemm g, const Sched& S, const Epi& E, const int tid) {
;     ...
;             PG8_WAIT_V(8); PG8_WAIT_L(0); PG8_BAR; PG8_MMA(0, 0, At, B0); PG8_MMA(0, 1, At, B1); PG8_BAR; PG8_SCHED;
;             PG8_LDA(At, 0, 1); PG8_STAGE(PG8_SB(0, 0), b2, voffB); PG8_STAGE(PG8_SB(0, 1), b2 + hstepB, voffB); PG8_STAGE(PG8_SA(0, 0), a2, voffA);
;             PG8_WAIT_V(8); PG8_WAIT_L(0); PG8_BAR; PG8_MMA(1, 0, At, B0); PG8_MMA(1, 1, At, B1); PG8_BAR; PG8_SCHED;
.Lkw_pl_0:
	s_waitcnt lgkmcnt(0)
	v_mfma_f32_16x16x32_bf16 v[124:127], v[148:151], v[208:211], v[124:127]
	v_mfma_f32_16x16x32_bf16 v[120:123], v[162:165], v[208:211], v[120:123]
	v_mfma_f32_16x16x32_bf16 v[108:111], v[148:151], v[216:219], v[108:111]
	v_mfma_f32_16x16x32_bf16 v[104:107], v[162:165], v[216:219], v[104:107]
	s_barrier
	s_setprio 1
	s_waitcnt lgkmcnt(0)
	v_mfma_f32_16x16x32_bf16 v[92:95], v[148:151], v[224:227], v[92:95]
	v_mfma_f32_16x16x32_bf16 v[88:91], v[162:165], v[224:227], v[88:91]
	v_mfma_f32_16x16x32_bf16 v[76:79], v[148:151], v[232:235], v[76:79]
	v_mfma_f32_16x16x32_bf16 v[72:75], v[162:165], v[232:235], v[72:75]
	v_mfma_f32_16x16x32_bf16 v[124:127], v[158:161], v[212:215], v[124:127]
	v_mfma_f32_16x16x32_bf16 v[120:123], v[188:191], v[212:215], v[120:123]
	v_mfma_f32_16x16x32_bf16 v[108:111], v[158:161], v[220:223], v[108:111]
	v_mfma_f32_16x16x32_bf16 v[104:107], v[188:191], v[220:223], v[104:107]
	v_mfma_f32_16x16x32_bf16 v[92:95], v[158:161], v[228:231], v[92:95]
	v_mfma_f32_16x16x32_bf16 v[88:91], v[188:191], v[228:231], v[88:91]
	v_mfma_f32_16x16x32_bf16 v[76:79], v[158:161], v[236:239], v[76:79]
	v_mfma_f32_16x16x32_bf16 v[72:75], v[188:191], v[236:239], v[72:75]
	s_setprio 0
	s_setprio 1
	v_mfma_f32_16x16x32_bf16 v[116:119], v[192:195], v[208:211], v[116:119]
	v_mfma_f32_16x16x32_bf16 v[112:115], v[200:203], v[208:211], v[112:115]
	v_mfma_f32_16x16x32_bf16 v[100:103], v[192:195], v[216:219], v[100:103]
	v_mfma_f32_16x16x32_bf16 v[96:99], v[200:203], v[216:219], v[96:99]
	v_mfma_f32_16x16x32_bf16 v[84:87], v[192:195], v[224:227], v[84:87]
	v_mfma_f32_16x16x32_bf16 v[80:83], v[200:203], v[224:227], v[80:83]
	v_mfma_f32_16x16x32_bf16 v[68:71], v[192:195], v[232:235], v[68:71]
	v_mfma_f32_16x16x32_bf16 v[64:67], v[200:203], v[232:235], v[64:67]
	v_mfma_f32_16x16x32_bf16 v[116:119], v[196:199], v[212:215], v[116:119]
	v_mfma_f32_16x16x32_bf16 v[112:115], v[204:207], v[212:215], v[112:115]
	v_mfma_f32_16x16x32_bf16 v[100:103], v[196:199], v[220:223], v[100:103]
	v_mfma_f32_16x16x32_bf16 v[96:99], v[204:207], v[220:223], v[96:99]
	v_mfma_f32_16x16x32_bf16 v[84:87], v[196:199], v[228:231], v[84:87]
	v_mfma_f32_16x16x32_bf16 v[80:83], v[204:207], v[228:231], v[80:83]
	v_mfma_f32_16x16x32_bf16 v[68:71], v[196:199], v[236:239], v[68:71]
	v_mfma_f32_16x16x32_bf16 v[64:67], v[204:207], v[236:239], v[64:67]
	s_setprio 0
	s_barrier
	s_add_i32 s50, s50, s81
	v_lshl_add_u64 v[166:167], s[48:49], 0, v[138:139]
	s_mov_b32 m0, s50
	ds_read_b128 v[208:211], v157 offset:16384
	ds_read_b128 v[212:215], v157 offset:17408
	ds_read_b128 v[216:219], v157 offset:18432
	ds_read_b128 v[220:223], v157 offset:19456
	ds_read_b128 v[224:227], v157 offset:20480
	ds_read_b128 v[228:231], v157 offset:21504
	ds_read_b128 v[232:235], v157 offset:22528
	ds_read_b128 v[236:239], v157 offset:23552
	global_load_lds_dwordx4 v[166:167], off
	s_add_i32 m0, s50, 0x2000
	v_lshl_add_u64 v[240:241], s[48:49], 0, v[142:143]
	s_add_u32 s48, s48, s21
	s_addc_u32 s49, s49, 0
	s_add_i32 s46, s46, s81
	global_load_lds_dwordx4 v[240:241], off
	v_lshl_add_u64 v[242:243], s[48:49], 0, v[138:139]
	s_mov_b32 m0, s46
	v_lshl_add_u64 v[244:245], s[48:49], 0, v[142:143]
	global_load_lds_dwordx4 v[242:243], off
	s_add_i32 m0, s46, 0x2000
	v_lshl_add_u64 v[246:247], s[92:93], 0, v[136:137]
	global_load_lds_dwordx4 v[244:245], off
	s_mov_b32 m0, s72
	v_lshl_add_u64 v[248:249], s[92:93], 0, v[140:141]
	global_load_lds_dwordx4 v[246:247], off
	s_mov_b32 m0, s73
	s_nop 0
	global_load_lds_dwordx4 v[248:249], off
	s_cmp_eq_u32 s99, 1
	s_cbranch_scc1 .Lkw_pl_1
	s_waitcnt vmcnt(8)
.Lkw_pl_1:
	s_waitcnt lgkmcnt(0)
	v_mfma_f32_16x16x32_bf16 v[60:63], v[148:151], v[208:211], v[60:63]
	v_mfma_f32_16x16x32_bf16 v[56:59], v[162:165], v[208:211], v[56:59]
	v_mfma_f32_16x16x32_bf16 v[44:47], v[148:151], v[216:219], v[44:47]
	v_mfma_f32_16x16x32_bf16 v[40:43], v[162:165], v[216:219], v[40:43]
	s_barrier
	s_setprio 1
	s_waitcnt lgkmcnt(0)
	v_mfma_f32_16x16x32_bf16 v[28:31], v[148:151], v[224:227], v[28:31]
	v_mfma_f32_16x16x32_bf16 v[24:27], v[162:165], v[224:227], v[24:27]
	v_mfma_f32_16x16x32_bf16 v[12:15], v[148:151], v[232:235], v[12:15]
	v_mfma_f32_16x16x32_bf16 v[8:11], v[162:165], v[232:235], v[8:11]
	v_mfma_f32_16x16x32_bf16 v[60:63], v[158:161], v[212:215], v[60:63]
	v_mfma_f32_16x16x32_bf16 v[56:59], v[188:191], v[212:215], v[56:59]
	v_mfma_f32_16x16x32_bf16 v[44:47], v[158:161], v[220:223], v[44:47]
	v_mfma_f32_16x16x32_bf16 v[40:43], v[188:191], v[220:223], v[40:43]
	v_mfma_f32_16x16x32_bf16 v[28:31], v[158:161], v[228:231], v[28:31]
	v_mfma_f32_16x16x32_bf16 v[24:27], v[188:191], v[228:231], v[24:27]
	v_mfma_f32_16x16x32_bf16 v[12:15], v[158:161], v[236:239], v[12:15]
	v_mfma_f32_16x16x32_bf16 v[8:11], v[188:191], v[236:239], v[8:11]
	s_setprio 0
	s_setprio 1
	v_mfma_f32_16x16x32_bf16 v[52:55], v[192:195], v[208:211], v[52:55]
	v_mfma_f32_16x16x32_bf16 v[48:51], v[200:203], v[208:211], v[48:51]
	v_mfma_f32_16x16x32_bf16 v[36:39], v[192:195], v[216:219], v[36:39]
	v_mfma_f32_16x16x32_bf16 v[32:35], v[200:203], v[216:219], v[32:35]
	v_mfma_f32_16x16x32_bf16 v[20:23], v[192:195], v[224:227], v[20:23]
	v_mfma_f32_16x16x32_bf16 v[16:19], v[200:203], v[224:227], v[16:19]
	v_mfma_f32_16x16x32_bf16 v[4:7], v[192:195], v[232:235], v[4:7]
	v_mfma_f32_16x16x32_bf16 v[0:3], v[200:203], v[232:235], v[0:3]
	v_mfma_f32_16x16x32_bf16 v[52:55], v[196:199], v[212:215], v[52:55]
	v_mfma_f32_16x16x32_bf16 v[48:51], v[204:207], v[212:215], v[48:51]
	v_mfma_f32_16x16x32_bf16 v[36:39], v[196:199], v[220:223], v[36:39]
	v_mfma_f32_16x16x32_bf16 v[32:35], v[204:207], v[220:223], v[32:35]
	v_mfma_f32_16x16x32_bf16 v[20:23], v[196:199], v[228:231], v[20:23]
	v_mfma_f32_16x16x32_bf16 v[16:19], v[204:207], v[228:231], v[16:19]
	v_mfma_f32_16x16x32_bf16 v[4:7], v[196:199], v[236:239], v[4:7]
	v_mfma_f32_16x16x32_bf16 v[0:3], v[204:207], v[236:239], v[0:3]
	s_setprio 0
	s_barrier
; #define PG8_STAGE(bufoff, gbase, voff) do { _Pragma("unroll") for (int _i = 0; _i < 2; ++_i) \
;         __builtin_amdgcn_global_load_lds((const unsigned*)((const char*)(gbase) + (voff)[_i]), (PG8_LAS unsigned*)(lds + (bufoff) + ldsw + _i * 8192), 16, 0, 0); } while (0)
; #define PG8_LDA(dst, b, h) do { _Pragma("unroll") for (int m = 0; m < 4; ++m) _Pragma("unroll") for (int k = 0; k < 2; ++k) dst[m][k] = *(const PG8_LAS bf16x8*)(lds + PG8_SA(b, h) + aoff + m * 2048 + k * 1024); } while (0)
; #define PG8_LDB(dst, b, h) do { _Pragma("unroll") for (int n = 0; n < 2; ++n) _Pragma("unroll") for (int k = 0; k < 2; ++k) dst[n][k] = *(const PG8_LAS bf16x8*)(lds + PG8_SB(b, h) + boff + n * 2048 + k * 1024); } while (0)
; #define PG8_MMA(ai, bj, At, Bt) do { __builtin_amdgcn_s_setprio(1); _Pragma("unroll") for (int m = 0; m < 4; ++m) _Pragma("unroll") for (int n = 0; n < 2; ++n) _Pragma("unroll") for (int k = 0; k < 2; ++k) \
;         acc[ai][bj][m][n] = __builtin_amdgcn_mfma_f32_16x16x32_bf16(Bt[n][k], At[m][k], acc[ai][bj][m][n], 0, 0, 0); __builtin_amdgcn_s_setprio(0); } while (0)
; #define PG8_WAIT_V(n) asm volatile("s_waitcnt vmcnt(" #n ")" ::: "memory")
; #define PG8_WAIT_L(n) asm volatile("s_waitcnt lgkmcnt(" #n ")" ::: "memory")
; #define PG8_BAR __builtin_amdgcn_s_barrier()
; #define PG8_SCHED __builtin_amdgcn_sched_barrier(0)
; template <class Epi, class Sched, bool ALIGN_EPI = false, bool SP2 = false>
; __device__ __forceinline__ void gemm_phase(PG8_LAS unsigned char* lds, const Gemm g, const Sched& S, const Epi& E, const int tid) {
;     ...
;             PG8_LDB(B0, 1, 0); PG8_LDB(B1, 1, 1); PG8_SCHED; PG8_LDA(At, 1, 0); PG8_STAGE(PG8_SA(0, 1), a2 + hstepA, voffA);
;             PG8_WAIT_V(8); PG8_WAIT_L(0); PG8_BAR; PG8_MMA(0, 0, At, B0); PG8_MMA(0, 1, At, B1); PG8_BAR; PG8_SCHED;
	s_add_i32 s46, 0, 0x18000
	v_add_u32_e32 v128, s46, v155
	s_add_i32 s50, 0, 0x1c000
	ds_read_b128 v[148:151], v128
	ds_read_b128 v[158:161], v128 offset:1024
	ds_read_b128 v[162:165], v128 offset:2048
	ds_read_b128 v[188:191], v128 offset:3072
	v_add_u32_e32 v128, s50, v155
	ds_read_b128 v[192:195], v128
	ds_read_b128 v[196:199], v128 offset:1024
	ds_read_b128 v[200:203], v128 offset:2048
	ds_read_b128 v[204:207], v128 offset:3072
	s_add_u32 s48, s92, s84
	s_addc_u32 s49, s93, 0
	s_mov_b32 m0, s24
	v_lshl_add_u64 v[250:251], s[48:49], 0, v[136:137]
	ds_read_b128 v[208:211], v157 offset:32768
	ds_read_b128 v[212:215], v157 offset:33792
	ds_read_b128 v[216:219], v157 offset:34816
	ds_read_b128 v[220:223], v157 offset:35840
	ds_read_b128 v[224:227], v157 offset:36864
	ds_read_b128 v[228:231], v157 offset:37888
	ds_read_b128 v[232:235], v157 offset:38912
	ds_read_b128 v[236:239], v157 offset:39936
	global_load_lds_dwordx4 v[250:251], off
	v_lshl_add_u64 v[250:251], s[48:49], 0, v[140:141]
	s_mov_b32 m0, s25
	s_nop 0
	global_load_lds_dwordx4 v[250:251], off
	s_waitcnt vmcnt(8)
	s_waitcnt lgkmcnt(0)
	v_mfma_f32_16x16x32_bf16 v[124:127], v[148:151], v[208:211], v[124:127]
	v_mfma_f32_16x16x32_bf16 v[120:123], v[162:165], v[208:211], v[120:123]
	v_mfma_f32_16x16x32_bf16 v[108:111], v[148:151], v[216:219], v[108:111]
	v_mfma_f32_16x16x32_bf16 v[104:107], v[162:165], v[216:219], v[104:107]
	s_barrier
	s_setprio 1
	s_waitcnt lgkmcnt(0)
	v_mfma_f32_16x16x32_bf16 v[92:95], v[148:151], v[224:227], v[92:95]
	v_mfma_f32_16x16x32_bf16 v[88:91], v[162:165], v[224:227], v[88:91]
	v_mfma_f32_16x16x32_bf16 v[76:79], v[148:151], v[232:235], v[76:79]
	v_mfma_f32_16x16x32_bf16 v[72:75], v[162:165], v[232:235], v[72:75]
	v_mfma_f32_16x16x32_bf16 v[124:127], v[158:161], v[212:215], v[124:127]
	v_mfma_f32_16x16x32_bf16 v[120:123], v[188:191], v[212:215], v[120:123]
	v_mfma_f32_16x16x32_bf16 v[108:111], v[158:161], v[220:223], v[108:111]
	v_mfma_f32_16x16x32_bf16 v[104:107], v[188:191], v[220:223], v[104:107]
	v_mfma_f32_16x16x32_bf16 v[92:95], v[158:161], v[228:231], v[92:95]
	v_mfma_f32_16x16x32_bf16 v[88:91], v[188:191], v[228:231], v[88:91]
	v_mfma_f32_16x16x32_bf16 v[76:79], v[158:161], v[236:239], v[76:79]
	v_mfma_f32_16x16x32_bf16 v[72:75], v[188:191], v[236:239], v[72:75]
	s_setprio 0
	s_setprio 1
	v_mfma_f32_16x16x32_bf16 v[116:119], v[192:195], v[208:211], v[116:119]
	v_mfma_f32_16x16x32_bf16 v[112:115], v[200:203], v[208:211], v[112:115]
	v_mfma_f32_16x16x32_bf16 v[100:103], v[192:195], v[216:219], v[100:103]
	v_mfma_f32_16x16x32_bf16 v[96:99], v[200:203], v[216:219], v[96:99]
	v_mfma_f32_16x16x32_bf16 v[84:87], v[192:195], v[224:227], v[84:87]
	v_mfma_f32_16x16x32_bf16 v[80:83], v[200:203], v[224:227], v[80:83]
	v_mfma_f32_16x16x32_bf16 v[68:71], v[192:195], v[232:235], v[68:71]
	v_mfma_f32_16x16x32_bf16 v[64:67], v[200:203], v[232:235], v[64:67]
	v_mfma_f32_16x16x32_bf16 v[116:119], v[196:199], v[212:215], v[116:119]
	v_mfma_f32_16x16x32_bf16 v[112:115], v[204:207], v[212:215], v[112:115]
	v_mfma_f32_16x16x32_bf16 v[100:103], v[196:199], v[220:223], v[100:103]
	v_mfma_f32_16x16x32_bf16 v[96:99], v[204:207], v[220:223], v[96:99]
	v_mfma_f32_16x16x32_bf16 v[84:87], v[196:199], v[228:231], v[84:87]
	v_mfma_f32_16x16x32_bf16 v[80:83], v[204:207], v[228:231], v[80:83]
	v_mfma_f32_16x16x32_bf16 v[68:71], v[196:199], v[236:239], v[68:71]
	v_mfma_f32_16x16x32_bf16 v[64:67], v[204:207], v[236:239], v[64:67]
	s_setprio 0
	s_barrier
; #define PG8_STAGE(bufoff, gbase, voff) do { _Pragma("unroll") for (int _i = 0; _i < 2; ++_i) \
;         __builtin_amdgcn_global_load_lds((const unsigned*)((const char*)(gbase) + (voff)[_i]), (PG8_LAS unsigned*)(lds + (bufoff) + ldsw + _i * 8192), 16, 0, 0); } while (0)
; #define PG8_LDA(dst, b, h) do { _Pragma("unroll") for (int m = 0; m < 4; ++m) _Pragma("unroll") for (int k = 0; k < 2; ++k) dst[m][k] = *(const PG8_LAS bf16x8*)(lds + PG8_SA(b, h) + aoff + m * 2048 + k * 1024); } while (0)
; #define PG8_MMA(ai, bj, At, Bt) do { __builtin_amdgcn_s_setprio(1); _Pragma("unroll") for (int m = 0; m < 4; ++m) _Pragma("unroll") for (int n = 0; n < 2; ++n) _Pragma("unroll") for (int k = 0; k < 2; ++k) \
;         acc[ai][bj][m][n] = __builtin_amdgcn_mfma_f32_16x16x32_bf16(Bt[n][k], At[m][k], acc[ai][bj][m][n], 0, 0, 0); __builtin_amdgcn_s_setprio(0); } while (0)
; #define PG8_WAIT_V(n) asm volatile("s_waitcnt vmcnt(" #n ")" ::: "memory")
; #define PG8_WAIT_L(n) asm volatile("s_waitcnt lgkmcnt(" #n ")" ::: "memory")
; #define PG8_BAR __builtin_amdgcn_s_barrier()
; #define PG8_SCHED __builtin_amdgcn_sched_barrier(0)
; template <class Epi, class Sched, bool ALIGN_EPI = false, bool SP2 = false>
; __device__ __forceinline__ void gemm_phase(PG8_LAS unsigned char* lds, const Gemm g, const Sched& S, const Epi& E, const int tid) {
;     ...
;         for (int t = 0; t < nt; t += 2) {
;     ...
;             PG8_LDA(At, 1, 1); PG8_STAGE(PG8_SB(1, 0), b3, voffB); PG8_STAGE(PG8_SB(1, 1), b3 + hstepB, voffB); PG8_STAGE(PG8_SA(1, 0), a3, voffA);
;             PG8_WAIT_V(8); PG8_WAIT_L(0); PG8_BAR; PG8_MMA(1, 0, At, B0); PG8_MMA(1, 1, At, B1); PG8_BAR; PG8_SCHED;
	s_add_i32 s46, s46, s81
	v_lshl_add_u64 v[166:167], v[166:167], 0, s[76:77]
	s_mov_b32 m0, s46
	ds_read_b128 v[208:211], v157 offset:49152
	ds_read_b128 v[212:215], v157 offset:50176
	ds_read_b128 v[216:219], v157 offset:51200
	ds_read_b128 v[220:223], v157 offset:52224
	ds_read_b128 v[224:227], v157 offset:53248
	ds_read_b128 v[228:231], v157 offset:54272
	ds_read_b128 v[232:235], v157 offset:55296
	ds_read_b128 v[236:239], v157 offset:56320
	global_load_lds_dwordx4 v[166:167], off
	v_lshl_add_u64 v[166:167], v[240:241], 0, s[76:77]
	s_add_i32 m0, s46, 0x2000
	s_add_i32 s46, s50, s81
	global_load_lds_dwordx4 v[166:167], off
	v_lshl_add_u64 v[166:167], v[242:243], 0, s[76:77]
	s_mov_b32 m0, s46
	s_nop 0
	global_load_lds_dwordx4 v[166:167], off
	v_lshl_add_u64 v[166:167], v[244:245], 0, s[76:77]
	s_add_i32 m0, s46, 0x2000
	s_nop 0
	global_load_lds_dwordx4 v[166:167], off
	v_lshl_add_u64 v[166:167], v[246:247], 0, s[76:77]
	s_mov_b32 m0, s27
	s_nop 0
	global_load_lds_dwordx4 v[166:167], off
	v_lshl_add_u64 v[166:167], v[248:249], 0, s[76:77]
	s_mov_b32 m0, s28
	s_nop 0
	global_load_lds_dwordx4 v[166:167], off
	s_waitcnt vmcnt(8)
	s_waitcnt lgkmcnt(0)
	v_mfma_f32_16x16x32_bf16 v[60:63], v[148:151], v[208:211], v[60:63]
	v_mfma_f32_16x16x32_bf16 v[56:59], v[162:165], v[208:211], v[56:59]
	v_mfma_f32_16x16x32_bf16 v[44:47], v[148:151], v[216:219], v[44:47]
	v_mfma_f32_16x16x32_bf16 v[40:43], v[162:165], v[216:219], v[40:43]
	s_barrier
	s_setprio 1
	s_waitcnt lgkmcnt(0)
	v_mfma_f32_16x16x32_bf16 v[28:31], v[148:151], v[224:227], v[28:31]
	v_mfma_f32_16x16x32_bf16 v[24:27], v[162:165], v[224:227], v[24:27]
	v_mfma_f32_16x16x32_bf16 v[12:15], v[148:151], v[232:235], v[12:15]
	v_mfma_f32_16x16x32_bf16 v[8:11], v[162:165], v[232:235], v[8:11]
	v_mfma_f32_16x16x32_bf16 v[60:63], v[158:161], v[212:215], v[60:63]
	v_mfma_f32_16x16x32_bf16 v[56:59], v[188:191], v[212:215], v[56:59]
	v_mfma_f32_16x16x32_bf16 v[44:47], v[158:161], v[220:223], v[44:47]
	v_mfma_f32_16x16x32_bf16 v[40:43], v[188:191], v[220:223], v[40:43]
	v_mfma_f32_16x16x32_bf16 v[28:31], v[158:161], v[228:231], v[28:31]
	v_mfma_f32_16x16x32_bf16 v[24:27], v[188:191], v[228:231], v[24:27]
	v_mfma_f32_16x16x32_bf16 v[12:15], v[158:161], v[236:239], v[12:15]
	v_mfma_f32_16x16x32_bf16 v[8:11], v[188:191], v[236:239], v[8:11]
	s_setprio 0
	s_setprio 1
	v_mfma_f32_16x16x32_bf16 v[52:55], v[192:195], v[208:211], v[52:55]
	v_mfma_f32_16x16x32_bf16 v[48:51], v[200:203], v[208:211], v[48:51]
	v_mfma_f32_16x16x32_bf16 v[36:39], v[192:195], v[216:219], v[36:39]
	v_mfma_f32_16x16x32_bf16 v[32:35], v[200:203], v[216:219], v[32:35]
	v_mfma_f32_16x16x32_bf16 v[20:23], v[192:195], v[224:227], v[20:23]
	v_mfma_f32_16x16x32_bf16 v[16:19], v[200:203], v[224:227], v[16:19]
	v_mfma_f32_16x16x32_bf16 v[4:7], v[192:195], v[232:235], v[4:7]
	v_mfma_f32_16x16x32_bf16 v[0:3], v[200:203], v[232:235], v[0:3]
	v_mfma_f32_16x16x32_bf16 v[52:55], v[196:199], v[212:215], v[52:55]
	v_mfma_f32_16x16x32_bf16 v[48:51], v[204:207], v[212:215], v[48:51]
	v_mfma_f32_16x16x32_bf16 v[36:39], v[196:199], v[220:223], v[36:39]
	v_mfma_f32_16x16x32_bf16 v[32:35], v[204:207], v[220:223], v[32:35]
	v_mfma_f32_16x16x32_bf16 v[20:23], v[196:199], v[228:231], v[20:23]
	v_mfma_f32_16x16x32_bf16 v[16:19], v[204:207], v[228:231], v[16:19]
	v_mfma_f32_16x16x32_bf16 v[4:7], v[196:199], v[236:239], v[4:7]
	v_mfma_f32_16x16x32_bf16 v[0:3], v[204:207], v[236:239], v[0:3]
	s_setprio 0
	s_barrier
	s_add_u32 s8, s8, 0x100
	s_addc_u32 s9, s9, 0
	s_add_u32 s44, s44, 0x100
	s_addc_u32 s45, s45, 0
	s_cmp_ge_u32 s47, s14
	s_mov_b32 s46, s47
	s_cbranch_scc0 .LBB0_468
	s_and_b64 vcc, exec, s[22:23]
	s_cbranch_vccz .LBB0_471
	s_barrier
